# hand-written cvt_mixer_a (both instances): four tiles / 32 loads per lane in flight per workgroup, same column maps
# baseline (speedup 1.0000x reference)
; #define LAS __attribute__((address_space(3)))
; __device__ __forceinline__ int otid(int wv0) { int t = (wv0 << 6) | olane(); asm volatile("" : "+v"(t)); return t; }
; __device__ __forceinline__ int rope_src(int j) { return (j & 1) ? 32 + (j >> 1) : (j >> 1); }
; #define CVT_LOAD(t_) do { const int k0_ = ((t_) % nkt) * 64, n0_ = ((t_) / nkt) * 64; const int sn = srcmap(kind, n0_ + nl); \
;     _Pragma("unroll") for (int i = 0; i < 8; ++i) { const int kl = kb + 8 * i; v[i] = 0.f; \
;       if (sn >= 0) { v[i] = src[(size_t)(k0_ + kl) * Nsrc + sn]; if (kscale) v[i] *= kscale[k0_ + kl]; } } } while (0)
; __device__ __forceinline__ int srcmap(int kind, int n) {
;   if (kind == 0) return n;
;   if (kind == 1) {
;     if (n < C_KR) return n;
;     if (n < C_HU) return 2304 + rope_src(n - C_KR);
;     if (n < C_CQ) return n - C_HU + 2368;
;     if (n < C_CKV) return n - C_CQ + 1280;
;     if (n < C_HV) return n - C_CKV + 1792;
;     if (n < LDH) return n;
;     return -1;
;   }
;   if (kind == 2) return 4416 + n;
;   if (kind == 4) { const int pn = n >> 8, lc = n & 255; return lc < 128 ? 128 * pn + lc : DFF + 128 * pn + (lc - 128); }
;   { const int hd = n / 192, c = n % 192; if (c < 128) return n; return hd * 192 + 128 + rope_src(c - 128); }
; }
; __device__ __forceinline__ void cvt_job(LAS unsigned char* lds, const float* src, bf16_t* dst, const float* kscale, int K, int Nsrc, int Ndst, int kind, int wv0, int bid_, int grd_) {
;   LAS float* tile = (LAS float*)lds;
;   const int tid = otid(wv0), nkt = K / 64, ntile = (Ndst / 64) * nkt;
;   if (bid_ < 0) return;
;   const int nl = tid & 63, kb = tid >> 6;
;   float v[8];
;     ...
;   if (bid_ < ntile) CVT_LOAD(bid_);
.LBB0_5:
	s_or_b64 exec, exec, s[2:3]
	s_load_dwordx2 s[16:17], s[54:55], 0x10
	s_waitcnt lgkmcnt(0)
	s_mov_b64 s[18:19], s[8:9]
	v_mbcnt_lo_u32_b32 v235, -1, 0
	v_mbcnt_hi_u32_b32 v235, -1, v235
	v_or_b32_e32 v235, s0, v235
	v_and_b32_e32 v236, 63, v235
	v_lshrrev_b32_e32 v216, 6, v235
	s_mov_b32 s30, 0xa500
	v_mul_lo_u32 v208, v216, s30
	v_lshrrev_b32_e32 v147, 1, v236
	v_and_b32_e32 v148, 1, v236
	v_lshl_add_u32 v147, v148, 5, v147
	v_lshl_add_u32 v146, v147, 2, v208
	v_lshl_add_u32 v208, v236, 2, v208
	v_add_u32_e32 v209, 0x52800, v208
	v_add_u32_e32 v210, 0xa5000, v208
	v_add_u32_e32 v211, 0xf7800, v208
	v_add_u32_e32 v212, 0x14a000, v208
	v_add_u32_e32 v213, 0x19c800, v208
	v_add_u32_e32 v214, 0x1ef000, v208
	v_add_u32_e32 v215, 0x241800, v208
	v_add_u32_e32 v147, 0x52800, v146
	v_add_u32_e32 v148, 0xa5000, v146
	v_add_u32_e32 v149, 0xf7800, v146
	v_add_u32_e32 v150, 0x14a000, v146
	v_add_u32_e32 v151, 0x19c800, v146
	v_add_u32_e32 v152, 0x1ef000, v146
	v_add_u32_e32 v153, 0x241800, v146
	v_mul_u32_u24_e32 v216, 65, v216
	v_add_lshl_u32 v216, v216, v236, 2
	v_and_b32_e32 v236, 7, v235
	v_lshlrev_b32_e32 v236, 3, v236
	v_lshrrev_b32_e32 v235, 3, v235
	v_mul_u32_u24_e32 v217, 65, v236
	v_add_lshl_u32 v217, v217, v235, 2
	s_movk_i32 s30, 0x800
	v_mul_lo_u32 v234, v235, s30
	v_add_lshl_u32 v234, v234, v236, 1
	s_mov_b32 s20, s82
	s_lshl_b32 s21, s60, 2
	s_mov_b32 s23, 0
	s_add_u32 s23, s23, s20
	s_and_b32 s28, s23, 31
	s_lshr_b32 s29, s23, 5
	s_lshl_b32 s28, s28, 6
	s_lshl_b32 s29, s29, 6
	s_mov_b32 s13, 0
	s_mov_b32 s31, s29
	s_add_u32 s12, s29, 0x400
	s_cmp_ge_u32 s29, 0x540
	s_cselect_b32 s31, s12, s31
	s_sub_u32 s12, s29, 0x440
	s_cmp_ge_u32 s29, 0x940
	s_cselect_b32 s31, s12, s31
	s_cmp_ge_u32 s29, 0xd40
	s_cselect_b32 s31, s29, s31
	s_cmp_eq_u32 s29, 0x500
	s_cselect_b32 s31, 0x900, s31
	s_cselect_b32 s13, 1, s13
	s_cmp_ge_u32 s29, 0x1140
	s_cselect_b32 s13, 2, s13
	s_cselect_b32 s31, 0, s31
	s_mul_i32 s12, s28, 0xa500
	s_lshl_b32 s31, s31, 2
	s_add_u32 s12, s12, s31
	s_add_u32 s24, s16, s12
	s_addc_u32 s25, s17, 0
	s_cmp_lt_u32 s23, 0x900
	s_cbranch_scc0 .Lmya_pl
	s_cmp_eq_u32 s13, 0
	s_cbranch_scc1 .Lmya_p1
	s_cmp_eq_u32 s13, 1
	s_cbranch_scc1 .Lmya_r1
	v_mov_b32_e32 v176, 0
	v_mov_b32_e32 v177, 0
	v_mov_b32_e32 v178, 0
	v_mov_b32_e32 v179, 0
	v_mov_b32_e32 v180, 0
	v_mov_b32_e32 v181, 0
	v_mov_b32_e32 v182, 0
	v_mov_b32_e32 v183, 0
	s_branch .Lmya_x1
.Lmya_r1:
	global_load_dword v176, v146, s[24:25]
	global_load_dword v177, v147, s[24:25]
	global_load_dword v178, v148, s[24:25]
	global_load_dword v179, v149, s[24:25]
	global_load_dword v180, v150, s[24:25]
	global_load_dword v181, v151, s[24:25]
	global_load_dword v182, v152, s[24:25]
	global_load_dword v183, v153, s[24:25]
	s_branch .Lmya_x1
.Lmya_p1:
	global_load_dword v176, v208, s[24:25]
	global_load_dword v177, v209, s[24:25]
	global_load_dword v178, v210, s[24:25]
	global_load_dword v179, v211, s[24:25]
	global_load_dword v180, v212, s[24:25]
	global_load_dword v181, v213, s[24:25]
	global_load_dword v182, v214, s[24:25]
	global_load_dword v183, v215, s[24:25]
.Lmya_x1:
	s_mul_i32 s23, s60, 1
	s_add_u32 s23, s23, s20
	s_and_b32 s28, s23, 31
	s_lshr_b32 s29, s23, 5
	s_lshl_b32 s28, s28, 6
	s_lshl_b32 s29, s29, 6
	s_mov_b32 s13, 0
	s_mov_b32 s31, s29
	s_add_u32 s12, s29, 0x400
	s_cmp_ge_u32 s29, 0x540
	s_cselect_b32 s31, s12, s31
	s_sub_u32 s12, s29, 0x440
	s_cmp_ge_u32 s29, 0x940
	s_cselect_b32 s31, s12, s31
	s_cmp_ge_u32 s29, 0xd40
	s_cselect_b32 s31, s29, s31
	s_cmp_eq_u32 s29, 0x500
	s_cselect_b32 s31, 0x900, s31
	s_cselect_b32 s13, 1, s13
	s_cmp_ge_u32 s29, 0x1140
	s_cselect_b32 s13, 2, s13
	s_cselect_b32 s31, 0, s31
	s_mul_i32 s12, s28, 0xa500
	s_lshl_b32 s31, s31, 2
	s_add_u32 s12, s12, s31
	s_add_u32 s24, s16, s12
	s_addc_u32 s25, s17, 0
	s_cmp_lt_u32 s23, 0x900
	s_cbranch_scc0 .Lmya_pl
	s_cmp_eq_u32 s13, 0
	s_cbranch_scc1 .Lmya_p2
	s_cmp_eq_u32 s13, 1
	s_cbranch_scc1 .Lmya_r2
	v_mov_b32_e32 v184, 0
	v_mov_b32_e32 v185, 0
	v_mov_b32_e32 v186, 0
	v_mov_b32_e32 v187, 0
	v_mov_b32_e32 v188, 0
	v_mov_b32_e32 v189, 0
	v_mov_b32_e32 v190, 0
	v_mov_b32_e32 v191, 0
	s_branch .Lmya_x2
.Lmya_r2:
	global_load_dword v184, v146, s[24:25]
	global_load_dword v185, v147, s[24:25]
	global_load_dword v186, v148, s[24:25]
	global_load_dword v187, v149, s[24:25]
	global_load_dword v188, v150, s[24:25]
	global_load_dword v189, v151, s[24:25]
	global_load_dword v190, v152, s[24:25]
	global_load_dword v191, v153, s[24:25]
	s_branch .Lmya_x2
.Lmya_p2:
	global_load_dword v184, v208, s[24:25]
	global_load_dword v185, v209, s[24:25]
	global_load_dword v186, v210, s[24:25]
	global_load_dword v187, v211, s[24:25]
	global_load_dword v188, v212, s[24:25]
	global_load_dword v189, v213, s[24:25]
	global_load_dword v190, v214, s[24:25]
	global_load_dword v191, v215, s[24:25]
.Lmya_x2:
	s_mul_i32 s23, s60, 2
	s_add_u32 s23, s23, s20
	s_and_b32 s28, s23, 31
	s_lshr_b32 s29, s23, 5
	s_lshl_b32 s28, s28, 6
	s_lshl_b32 s29, s29, 6
	s_mov_b32 s13, 0
	s_mov_b32 s31, s29
	s_add_u32 s12, s29, 0x400
	s_cmp_ge_u32 s29, 0x540
	s_cselect_b32 s31, s12, s31
	s_sub_u32 s12, s29, 0x440
	s_cmp_ge_u32 s29, 0x940
	s_cselect_b32 s31, s12, s31
	s_cmp_ge_u32 s29, 0xd40
	s_cselect_b32 s31, s29, s31
	s_cmp_eq_u32 s29, 0x500
	s_cselect_b32 s31, 0x900, s31
	s_cselect_b32 s13, 1, s13
	s_cmp_ge_u32 s29, 0x1140
	s_cselect_b32 s13, 2, s13
	s_cselect_b32 s31, 0, s31
	s_mul_i32 s12, s28, 0xa500
	s_lshl_b32 s31, s31, 2
	s_add_u32 s12, s12, s31
	s_add_u32 s24, s16, s12
	s_addc_u32 s25, s17, 0
	s_cmp_lt_u32 s23, 0x900
	s_cbranch_scc0 .Lmya_pl
	s_cmp_eq_u32 s13, 0
	s_cbranch_scc1 .Lmya_p3
	s_cmp_eq_u32 s13, 1
	s_cbranch_scc1 .Lmya_r3
	v_mov_b32_e32 v192, 0
	v_mov_b32_e32 v193, 0
	v_mov_b32_e32 v194, 0
	v_mov_b32_e32 v195, 0
	v_mov_b32_e32 v196, 0
	v_mov_b32_e32 v197, 0
	v_mov_b32_e32 v198, 0
	v_mov_b32_e32 v199, 0
	s_branch .Lmya_x3
; #define CVT_LOAD(t_) do { const int k0_ = ((t_) % nkt) * 64, n0_ = ((t_) / nkt) * 64; const int sn = srcmap(kind, n0_ + nl); \
;     _Pragma("unroll") for (int i = 0; i < 8; ++i) { const int kl = kb + 8 * i; v[i] = 0.f; \
;       if (sn >= 0) { v[i] = src[(size_t)(k0_ + kl) * Nsrc + sn]; if (kscale) v[i] *= kscale[k0_ + kl]; } } } while (0)
; __device__ __forceinline__ void cvt_job(LAS unsigned char* lds, const float* src, bf16_t* dst, const float* kscale, int K, int Nsrc, int Ndst, int kind, int wv0, int bid_, int grd_) {
;     ...
;   if (bid_ < ntile) CVT_LOAD(bid_);
;   for (int t = bid_; t < ntile; t += grd_) {
;     const int k0 = (t % nkt) * 64, n0 = (t / nkt) * 64;
; #pragma unroll
;     for (int i = 0; i < 8; ++i) tile[(kb + 8 * i) * 65 + nl] = v[i];
;     __syncthreads();
;     if (t + grd_ < ntile) CVT_LOAD(t + grd_);
.Lmya_r3:
	global_load_dword v192, v146, s[24:25]
	global_load_dword v193, v147, s[24:25]
	global_load_dword v194, v148, s[24:25]
	global_load_dword v195, v149, s[24:25]
	global_load_dword v196, v150, s[24:25]
	global_load_dword v197, v151, s[24:25]
	global_load_dword v198, v152, s[24:25]
	global_load_dword v199, v153, s[24:25]
	s_branch .Lmya_x3
.Lmya_p3:
	global_load_dword v192, v208, s[24:25]
	global_load_dword v193, v209, s[24:25]
	global_load_dword v194, v210, s[24:25]
	global_load_dword v195, v211, s[24:25]
	global_load_dword v196, v212, s[24:25]
	global_load_dword v197, v213, s[24:25]
	global_load_dword v198, v214, s[24:25]
	global_load_dword v199, v215, s[24:25]
.Lmya_x3:
	s_mul_i32 s23, s60, 3
	s_add_u32 s23, s23, s20
	s_and_b32 s28, s23, 31
	s_lshr_b32 s29, s23, 5
	s_lshl_b32 s28, s28, 6
	s_lshl_b32 s29, s29, 6
	s_mov_b32 s13, 0
	s_mov_b32 s31, s29
	s_add_u32 s12, s29, 0x400
	s_cmp_ge_u32 s29, 0x540
	s_cselect_b32 s31, s12, s31
	s_sub_u32 s12, s29, 0x440
	s_cmp_ge_u32 s29, 0x940
	s_cselect_b32 s31, s12, s31
	s_cmp_ge_u32 s29, 0xd40
	s_cselect_b32 s31, s29, s31
	s_cmp_eq_u32 s29, 0x500
	s_cselect_b32 s31, 0x900, s31
	s_cselect_b32 s13, 1, s13
	s_cmp_ge_u32 s29, 0x1140
	s_cselect_b32 s13, 2, s13
	s_cselect_b32 s31, 0, s31
	s_mul_i32 s12, s28, 0xa500
	s_lshl_b32 s31, s31, 2
	s_add_u32 s12, s12, s31
	s_add_u32 s24, s16, s12
	s_addc_u32 s25, s17, 0
	s_cmp_lt_u32 s23, 0x900
	s_cbranch_scc0 .Lmya_pl
	s_cmp_eq_u32 s13, 0
	s_cbranch_scc1 .Lmya_p4
	s_cmp_eq_u32 s13, 1
	s_cbranch_scc1 .Lmya_r4
	v_mov_b32_e32 v200, 0
	v_mov_b32_e32 v201, 0
	v_mov_b32_e32 v202, 0
	v_mov_b32_e32 v203, 0
	v_mov_b32_e32 v204, 0
	v_mov_b32_e32 v205, 0
	v_mov_b32_e32 v206, 0
	v_mov_b32_e32 v207, 0
	s_branch .Lmya_x4
.Lmya_r4:
	global_load_dword v200, v146, s[24:25]
	global_load_dword v201, v147, s[24:25]
	global_load_dword v202, v148, s[24:25]
	global_load_dword v203, v149, s[24:25]
	global_load_dword v204, v150, s[24:25]
	global_load_dword v205, v151, s[24:25]
	global_load_dword v206, v152, s[24:25]
	global_load_dword v207, v153, s[24:25]
	s_branch .Lmya_x4
.Lmya_p4:
	global_load_dword v200, v208, s[24:25]
	global_load_dword v201, v209, s[24:25]
	global_load_dword v202, v210, s[24:25]
	global_load_dword v203, v211, s[24:25]
	global_load_dword v204, v212, s[24:25]
	global_load_dword v205, v213, s[24:25]
	global_load_dword v206, v214, s[24:25]
	global_load_dword v207, v215, s[24:25]
.Lmya_x4:
.Lmya_pl:
	s_waitcnt vmcnt(0)
.Lmya_loop:
	s_mov_b32 s23, 0
	s_add_u32 s23, s23, s20
	s_cmp_lt_u32 s23, 0x900
	s_cbranch_scc0 .Lmya_wd
	ds_write_b32 v216, v176 offset:0
	ds_write_b32 v216, v177 offset:2080
	ds_write_b32 v216, v178 offset:4160
	ds_write_b32 v216, v179 offset:6240
	ds_write_b32 v216, v180 offset:8320
	ds_write_b32 v216, v181 offset:10400
	ds_write_b32 v216, v182 offset:12480
	ds_write_b32 v216, v183 offset:14560
	s_mul_i32 s23, s60, 1
	s_add_u32 s23, s23, s20
	s_cmp_lt_u32 s23, 0x900
	s_cbranch_scc0 .Lmya_wd
	ds_write_b32 v216, v184 offset:16640
	ds_write_b32 v216, v185 offset:18720
	ds_write_b32 v216, v186 offset:20800
	ds_write_b32 v216, v187 offset:22880
	ds_write_b32 v216, v188 offset:24960
	ds_write_b32 v216, v189 offset:27040
	ds_write_b32 v216, v190 offset:29120
	ds_write_b32 v216, v191 offset:31200
	s_mul_i32 s23, s60, 2
	s_add_u32 s23, s23, s20
	s_cmp_lt_u32 s23, 0x900
	s_cbranch_scc0 .Lmya_wd
	ds_write_b32 v216, v192 offset:33280
	ds_write_b32 v216, v193 offset:35360
	ds_write_b32 v216, v194 offset:37440
	ds_write_b32 v216, v195 offset:39520
	ds_write_b32 v216, v196 offset:41600
	ds_write_b32 v216, v197 offset:43680
	ds_write_b32 v216, v198 offset:45760
	ds_write_b32 v216, v199 offset:47840
	s_mul_i32 s23, s60, 3
	s_add_u32 s23, s23, s20
	s_cmp_lt_u32 s23, 0x900
	s_cbranch_scc0 .Lmya_wd
	ds_write_b32 v216, v200 offset:49920
	ds_write_b32 v216, v201 offset:52000
	ds_write_b32 v216, v202 offset:54080
	ds_write_b32 v216, v203 offset:56160
	ds_write_b32 v216, v204 offset:58240
	ds_write_b32 v216, v205 offset:60320
	ds_write_b32 v216, v206 offset:62400
	ds_write_b32 v216, v207 offset:64480
.Lmya_wd:
	s_waitcnt lgkmcnt(0)
	s_barrier
	s_add_u32 s20, s20, s21
	s_mov_b32 s23, 0
	s_add_u32 s23, s23, s20
	s_and_b32 s28, s23, 31
	s_lshr_b32 s29, s23, 5
	s_lshl_b32 s28, s28, 6
	s_lshl_b32 s29, s29, 6
	s_mov_b32 s13, 0
	s_mov_b32 s31, s29
	s_add_u32 s12, s29, 0x400
	s_cmp_ge_u32 s29, 0x540
	s_cselect_b32 s31, s12, s31
	s_sub_u32 s12, s29, 0x440
	s_cmp_ge_u32 s29, 0x940
	s_cselect_b32 s31, s12, s31
	s_cmp_ge_u32 s29, 0xd40
	s_cselect_b32 s31, s29, s31
	s_cmp_eq_u32 s29, 0x500
	s_cselect_b32 s31, 0x900, s31
	s_cselect_b32 s13, 1, s13
	s_cmp_ge_u32 s29, 0x1140
	s_cselect_b32 s13, 2, s13
	s_cselect_b32 s31, 0, s31
	s_mul_i32 s12, s28, 0xa500
	s_lshl_b32 s31, s31, 2
	s_add_u32 s12, s12, s31
	s_add_u32 s24, s16, s12
	s_addc_u32 s25, s17, 0
	s_cmp_lt_u32 s23, 0x900
	s_cbranch_scc0 .Lmya_nl
	s_cmp_eq_u32 s13, 0
	s_cbranch_scc1 .Lmya_p5
	s_cmp_eq_u32 s13, 1
	s_cbranch_scc1 .Lmya_r5
	v_mov_b32_e32 v176, 0
	v_mov_b32_e32 v177, 0
	v_mov_b32_e32 v178, 0
	v_mov_b32_e32 v179, 0
	v_mov_b32_e32 v180, 0
	v_mov_b32_e32 v181, 0
	v_mov_b32_e32 v182, 0
	v_mov_b32_e32 v183, 0
	s_branch .Lmya_x5

; __device__ __forceinline__ void cvt_job(LAS unsigned char* lds, const float* src, bf16_t* dst, const float* kscale, int K, int Nsrc, int Ndst, int kind, int wv0, int bid_, int grd_) {
;     ...
;     { const int nl2 = tid >> 3, kc = (tid & 7) * 8; float w[8];
; #pragma unroll
;       for (int j = 0; j < 8; ++j) w[j] = tile[(kc + j) * 65 + nl2];
;       store8bf(dst + (size_t)(n0 + nl2) * K + k0 + kc, w); }
;     __syncthreads();
;   }
.Lmya_x8:
.Lmya_nl:
	s_sub_u32 s20, s20, s21
	s_mov_b32 s23, 0
	s_add_u32 s23, s23, s20
	s_and_b32 s28, s23, 31
	s_lshr_b32 s29, s23, 5
	s_lshl_b32 s28, s28, 6
	s_lshl_b32 s29, s29, 6
	s_mul_i32 s12, s29, 0x800
	s_add_u32 s12, s12, s28
	s_lshl_b32 s12, s12, 1
	s_add_u32 s26, s18, s12
	s_addc_u32 s27, s19, 0
	s_cmp_lt_u32 s23, 0x900
	s_cbranch_scc0 .Lmya_sd
	ds_read_b32 v98, v217 offset:0
	ds_read_b32 v99, v217 offset:260
	ds_read_b32 v100, v217 offset:520
	ds_read_b32 v101, v217 offset:780
	ds_read_b32 v102, v217 offset:1040
	ds_read_b32 v103, v217 offset:1300
	ds_read_b32 v104, v217 offset:1560
	ds_read_b32 v105, v217 offset:1820
	s_waitcnt lgkmcnt(0)
	v_cvt_pk_bf16_f32 v130, v98, v99
	v_cvt_pk_bf16_f32 v131, v100, v101
	v_cvt_pk_bf16_f32 v132, v102, v103
	v_cvt_pk_bf16_f32 v133, v104, v105
	global_store_dwordx4 v234, v[130:133], s[26:27]
	s_mul_i32 s23, s60, 1
	s_add_u32 s23, s23, s20
	s_and_b32 s28, s23, 31
	s_lshr_b32 s29, s23, 5
	s_lshl_b32 s28, s28, 6
	s_lshl_b32 s29, s29, 6
	s_mul_i32 s12, s29, 0x800
	s_add_u32 s12, s12, s28
	s_lshl_b32 s12, s12, 1
	s_add_u32 s26, s18, s12
	s_addc_u32 s27, s19, 0
	s_cmp_lt_u32 s23, 0x900
	s_cbranch_scc0 .Lmya_sd
	ds_read_b32 v106, v217 offset:16640
	ds_read_b32 v107, v217 offset:16900
	ds_read_b32 v108, v217 offset:17160
	ds_read_b32 v109, v217 offset:17420
	ds_read_b32 v110, v217 offset:17680
	ds_read_b32 v111, v217 offset:17940
	ds_read_b32 v112, v217 offset:18200
	ds_read_b32 v113, v217 offset:18460
	s_waitcnt lgkmcnt(0)
	v_cvt_pk_bf16_f32 v134, v106, v107
	v_cvt_pk_bf16_f32 v135, v108, v109
	v_cvt_pk_bf16_f32 v136, v110, v111
	v_cvt_pk_bf16_f32 v137, v112, v113
	global_store_dwordx4 v234, v[134:137], s[26:27]
	s_mul_i32 s23, s60, 2
	s_add_u32 s23, s23, s20
	s_and_b32 s28, s23, 31
	s_lshr_b32 s29, s23, 5
	s_lshl_b32 s28, s28, 6
	s_lshl_b32 s29, s29, 6
	s_mul_i32 s12, s29, 0x800
	s_add_u32 s12, s12, s28
	s_lshl_b32 s12, s12, 1
	s_add_u32 s26, s18, s12
	s_addc_u32 s27, s19, 0
	s_cmp_lt_u32 s23, 0x900
	s_cbranch_scc0 .Lmya_sd
	ds_read_b32 v114, v217 offset:33280
	ds_read_b32 v115, v217 offset:33540
	ds_read_b32 v116, v217 offset:33800
	ds_read_b32 v117, v217 offset:34060
	ds_read_b32 v118, v217 offset:34320
	ds_read_b32 v119, v217 offset:34580
	ds_read_b32 v120, v217 offset:34840
	ds_read_b32 v121, v217 offset:35100
	s_waitcnt lgkmcnt(0)
	v_cvt_pk_bf16_f32 v138, v114, v115
	v_cvt_pk_bf16_f32 v139, v116, v117
	v_cvt_pk_bf16_f32 v140, v118, v119
	v_cvt_pk_bf16_f32 v141, v120, v121
	global_store_dwordx4 v234, v[138:141], s[26:27]
	s_mul_i32 s23, s60, 3
	s_add_u32 s23, s23, s20
	s_and_b32 s28, s23, 31
	s_lshr_b32 s29, s23, 5
	s_lshl_b32 s28, s28, 6
	s_lshl_b32 s29, s29, 6
	s_mul_i32 s12, s29, 0x800
	s_add_u32 s12, s12, s28
	s_lshl_b32 s12, s12, 1
	s_add_u32 s26, s18, s12
	s_addc_u32 s27, s19, 0
	s_cmp_lt_u32 s23, 0x900
	s_cbranch_scc0 .Lmya_sd
	ds_read_b32 v122, v217 offset:49920
	ds_read_b32 v123, v217 offset:50180
	ds_read_b32 v124, v217 offset:50440
	ds_read_b32 v125, v217 offset:50700
	ds_read_b32 v126, v217 offset:50960
	ds_read_b32 v127, v217 offset:51220
	ds_read_b32 v128, v217 offset:51480
	ds_read_b32 v129, v217 offset:51740
	s_waitcnt lgkmcnt(0)
	v_cvt_pk_bf16_f32 v142, v122, v123
	v_cvt_pk_bf16_f32 v143, v124, v125
	v_cvt_pk_bf16_f32 v144, v126, v127
	v_cvt_pk_bf16_f32 v145, v128, v129
	global_store_dwordx4 v234, v[142:145], s[26:27]
.Lmya_sd:
	s_barrier
	s_add_u32 s20, s20, s21
	s_cmp_lt_u32 s20, 0x900
	s_cbranch_scc0 .Lmya_end
	s_waitcnt vmcnt(4)
	s_branch .Lmya_loop
; #define LAS __attribute__((address_space(3)))
; __device__ __forceinline__ int otid(int wv0) { int t = (wv0 << 6) | olane(); asm volatile("" : "+v"(t)); return t; }
; __device__ __forceinline__ int obid() { int b = blockIdx.x; asm volatile("" : "+s"(b)); return b; }
; __device__ __forceinline__ int ogrid() { int g = gridDim.x; asm volatile("" : "+s"(g)); return g; }
; #define CVT_LOAD(t_) do { const int k0_ = ((t_) % nkt) * 64, n0_ = ((t_) / nkt) * 64; const int sn = srcmap(kind, n0_ + nl); \
;     _Pragma("unroll") for (int i = 0; i < 8; ++i) { const int kl = kb + 8 * i; v[i] = 0.f; \
;       if (sn >= 0) { v[i] = src[(size_t)(k0_ + kl) * Nsrc + sn]; if (kscale) v[i] *= kscale[k0_ + kl]; } } } while (0)
; __device__ __forceinline__ void cvt_job(LAS unsigned char* lds, const float* src, bf16_t* dst, const float* kscale, int K, int Nsrc, int Ndst, int kind, int wv0, int bid_, int grd_) {
;   LAS float* tile = (LAS float*)lds;
;   const int tid = otid(wv0), nkt = K / 64, ntile = (Ndst / 64) * nkt;
;   if (bid_ < 0) return;
;   const int nl = tid & 63, kb = tid >> 6;
;   float v[8];
;     ...
;   if (bid_ < ntile) CVT_LOAD(bid_);
; __device__ __forceinline__ void prologue(KP p, int wv0) {
;   const size_t tid = (size_t)obid() * 512 + otid(wv0), nth = (size_t)ogrid() * 512;
;   bf16_t* xb = (bf16_t*)(p->ws + O_XB);
;   for (size_t i = tid; i < (size_t)NTOK * DM / 4; i += 4 * nth) {
;     f32x4 v[4];
; #pragma unroll
;     for (int j = 0; j < 4; ++j) if (i + j * nth < (size_t)NTOK * DM / 4) v[j] = ((const f32x4*)p->x)[i + j * nth];
; #pragma unroll
;     for (int j = 0; j < 4; ++j) if (i + j * nth < (size_t)NTOK * DM / 4) { u32x2 w; w.x = pk2(v[j][0], v[j][1]); w.y = pk2(v[j][2], v[j][3]); ((u32x2*)xb)[i + j * nth] = w; } }
.Lmya_end:
	s_waitcnt vmcnt(0)
	s_add_u32 s18, s8, 0x1200000
	s_addc_u32 s19, s9, 0
	v_mbcnt_lo_u32_b32 v235, -1, 0
	v_mbcnt_hi_u32_b32 v235, -1, v235
	v_or_b32_e32 v235, s0, v235
	v_and_b32_e32 v236, 63, v235
	v_lshrrev_b32_e32 v216, 6, v235
	s_mov_b32 s30, 0xa500
	v_mul_lo_u32 v208, v216, s30
	v_lshl_add_u32 v208, v236, 2, v208
	v_add_u32_e32 v209, 0x52800, v208
	v_add_u32_e32 v210, 0xa5000, v208
	v_add_u32_e32 v211, 0xf7800, v208
	v_add_u32_e32 v212, 0x14a000, v208
	v_add_u32_e32 v213, 0x19c800, v208
	v_add_u32_e32 v214, 0x1ef000, v208
	v_add_u32_e32 v215, 0x241800, v208
	v_mul_u32_u24_e32 v216, 65, v216
	v_add_lshl_u32 v216, v216, v236, 2
	v_and_b32_e32 v236, 7, v235
	v_lshlrev_b32_e32 v236, 3, v236
	v_lshrrev_b32_e32 v235, 3, v235
	v_mul_u32_u24_e32 v217, 65, v236
	v_add_lshl_u32 v217, v217, v235, 2
	s_movk_i32 s30, 0x800
	v_mul_lo_u32 v234, v235, s30
	v_add_lshl_u32 v234, v234, v236, 1
	s_mov_b32 s20, s82
	s_lshl_b32 s21, s60, 2
	s_mov_b32 s23, 0
	s_add_u32 s23, s23, s20
	s_and_b32 s28, s23, 31
	s_lshr_b32 s29, s23, 5
	s_lshl_b32 s28, s28, 6
	s_lshl_b32 s29, s29, 6
	s_mov_b32 s13, 0
	s_add_u32 s31, s29, 0x1140
	s_mul_i32 s12, s28, 0xa500
	s_lshl_b32 s31, s31, 2
	s_add_u32 s12, s12, s31
	s_add_u32 s24, s16, s12
	s_addc_u32 s25, s17, 0
	s_cmp_lt_u32 s23, 0xc00
	s_cbranch_scc0 .Lmyg_pl
	global_load_dword v176, v208, s[24:25]
	global_load_dword v177, v209, s[24:25]
	global_load_dword v178, v210, s[24:25]
	global_load_dword v179, v211, s[24:25]
	global_load_dword v180, v212, s[24:25]
	global_load_dword v181, v213, s[24:25]
	global_load_dword v182, v214, s[24:25]
	global_load_dword v183, v215, s[24:25]
	s_mul_i32 s23, s60, 1
	s_add_u32 s23, s23, s20
	s_and_b32 s28, s23, 31
	s_lshr_b32 s29, s23, 5
	s_lshl_b32 s28, s28, 6
	s_lshl_b32 s29, s29, 6
	s_mov_b32 s13, 0
	s_add_u32 s31, s29, 0x1140
	s_mul_i32 s12, s28, 0xa500
	s_lshl_b32 s31, s31, 2
	s_add_u32 s12, s12, s31
	s_add_u32 s24, s16, s12
	s_addc_u32 s25, s17, 0
	s_cmp_lt_u32 s23, 0xc00
	s_cbranch_scc0 .Lmyg_pl
	global_load_dword v184, v208, s[24:25]
	global_load_dword v185, v209, s[24:25]
	global_load_dword v186, v210, s[24:25]
	global_load_dword v187, v211, s[24:25]
	global_load_dword v188, v212, s[24:25]
	global_load_dword v189, v213, s[24:25]
	global_load_dword v190, v214, s[24:25]
	global_load_dword v191, v215, s[24:25]
	s_mul_i32 s23, s60, 2
	s_add_u32 s23, s23, s20
	s_and_b32 s28, s23, 31
	s_lshr_b32 s29, s23, 5
	s_lshl_b32 s28, s28, 6
	s_lshl_b32 s29, s29, 6
	s_mov_b32 s13, 0
	s_add_u32 s31, s29, 0x1140
	s_mul_i32 s12, s28, 0xa500
	s_lshl_b32 s31, s31, 2
	s_add_u32 s12, s12, s31
	s_add_u32 s24, s16, s12
	s_addc_u32 s25, s17, 0
	s_cmp_lt_u32 s23, 0xc00
	s_cbranch_scc0 .Lmyg_pl
	global_load_dword v192, v208, s[24:25]
	global_load_dword v193, v209, s[24:25]
	global_load_dword v194, v210, s[24:25]
	global_load_dword v195, v211, s[24:25]
	global_load_dword v196, v212, s[24:25]
	global_load_dword v197, v213, s[24:25]
	global_load_dword v198, v214, s[24:25]
	global_load_dword v199, v215, s[24:25]
	s_mul_i32 s23, s60, 3
	s_add_u32 s23, s23, s20
	s_and_b32 s28, s23, 31
	s_lshr_b32 s29, s23, 5
	s_lshl_b32 s28, s28, 6
	s_lshl_b32 s29, s29, 6
	s_mov_b32 s13, 0
	s_add_u32 s31, s29, 0x1140
	s_mul_i32 s12, s28, 0xa500
	s_lshl_b32 s31, s31, 2
	s_add_u32 s12, s12, s31
	s_add_u32 s24, s16, s12
	s_addc_u32 s25, s17, 0
	s_cmp_lt_u32 s23, 0xc00
	s_cbranch_scc0 .Lmyg_pl
	global_load_dword v200, v208, s[24:25]
	global_load_dword v201, v209, s[24:25]
	global_load_dword v202, v210, s[24:25]
	global_load_dword v203, v211, s[24:25]
	global_load_dword v204, v212, s[24:25]
	global_load_dword v205, v213, s[24:25]
	global_load_dword v206, v214, s[24:25]
	global_load_dword v207, v215, s[24:25]

; #define CVT_LOAD(t_) do { const int k0_ = ((t_) % nkt) * 64, n0_ = ((t_) / nkt) * 64; const int sn = srcmap(kind, n0_ + nl); \
;     _Pragma("unroll") for (int i = 0; i < 8; ++i) { const int kl = kb + 8 * i; v[i] = 0.f; \
;       if (sn >= 0) { v[i] = src[(size_t)(k0_ + kl) * Nsrc + sn]; if (kscale) v[i] *= kscale[k0_ + kl]; } } } while (0)
; __device__ __forceinline__ void cvt_job(LAS unsigned char* lds, const float* src, bf16_t* dst, const float* kscale, int K, int Nsrc, int Ndst, int kind, int wv0, int bid_, int grd_) {
;     ...
;   for (int t = bid_; t < ntile; t += grd_) {
;     const int k0 = (t % nkt) * 64, n0 = (t / nkt) * 64;
; #pragma unroll
;     for (int i = 0; i < 8; ++i) tile[(kb + 8 * i) * 65 + nl] = v[i];
;     __syncthreads();
;     if (t + grd_ < ntile) CVT_LOAD(t + grd_);
.Lmyg_loop:
	s_mov_b32 s23, 0
	s_add_u32 s23, s23, s20
	s_cmp_lt_u32 s23, 0xc00
	s_cbranch_scc0 .Lmyg_wd
	ds_write_b32 v216, v176 offset:0
	ds_write_b32 v216, v177 offset:2080
	ds_write_b32 v216, v178 offset:4160
	ds_write_b32 v216, v179 offset:6240
	ds_write_b32 v216, v180 offset:8320
	ds_write_b32 v216, v181 offset:10400
	ds_write_b32 v216, v182 offset:12480
	ds_write_b32 v216, v183 offset:14560
	s_mul_i32 s23, s60, 1
	s_add_u32 s23, s23, s20
	s_cmp_lt_u32 s23, 0xc00
	s_cbranch_scc0 .Lmyg_wd
	ds_write_b32 v216, v184 offset:16640
	ds_write_b32 v216, v185 offset:18720
	ds_write_b32 v216, v186 offset:20800
	ds_write_b32 v216, v187 offset:22880
	ds_write_b32 v216, v188 offset:24960
	ds_write_b32 v216, v189 offset:27040
	ds_write_b32 v216, v190 offset:29120
	ds_write_b32 v216, v191 offset:31200
	s_mul_i32 s23, s60, 2
	s_add_u32 s23, s23, s20
	s_cmp_lt_u32 s23, 0xc00
	s_cbranch_scc0 .Lmyg_wd
	ds_write_b32 v216, v192 offset:33280
	ds_write_b32 v216, v193 offset:35360
	ds_write_b32 v216, v194 offset:37440
	ds_write_b32 v216, v195 offset:39520
	ds_write_b32 v216, v196 offset:41600
	ds_write_b32 v216, v197 offset:43680
	ds_write_b32 v216, v198 offset:45760
	ds_write_b32 v216, v199 offset:47840
	s_mul_i32 s23, s60, 3
	s_add_u32 s23, s23, s20
	s_cmp_lt_u32 s23, 0xc00
	s_cbranch_scc0 .Lmyg_wd
	ds_write_b32 v216, v200 offset:49920
	ds_write_b32 v216, v201 offset:52000
	ds_write_b32 v216, v202 offset:54080
	ds_write_b32 v216, v203 offset:56160
	ds_write_b32 v216, v204 offset:58240
	ds_write_b32 v216, v205 offset:60320
	ds_write_b32 v216, v206 offset:62400
	ds_write_b32 v216, v207 offset:64480
.Lmyg_wd:
	s_waitcnt lgkmcnt(0)
	s_barrier
	s_add_u32 s20, s20, s21
	s_mov_b32 s23, 0
	s_add_u32 s23, s23, s20
	s_and_b32 s28, s23, 31
	s_lshr_b32 s29, s23, 5
	s_lshl_b32 s28, s28, 6
	s_lshl_b32 s29, s29, 6
	s_mov_b32 s13, 0
	s_add_u32 s31, s29, 0x1140
	s_mul_i32 s12, s28, 0xa500
	s_lshl_b32 s31, s31, 2
	s_add_u32 s12, s12, s31
	s_add_u32 s24, s16, s12
	s_addc_u32 s25, s17, 0
	s_cmp_lt_u32 s23, 0xc00
	s_cbranch_scc0 .Lmyg_nl
	global_load_dword v176, v208, s[24:25]
	global_load_dword v177, v209, s[24:25]
	global_load_dword v178, v210, s[24:25]
	global_load_dword v179, v211, s[24:25]
	global_load_dword v180, v212, s[24:25]
	global_load_dword v181, v213, s[24:25]
	global_load_dword v182, v214, s[24:25]
	global_load_dword v183, v215, s[24:25]
	s_mul_i32 s23, s60, 1
	s_add_u32 s23, s23, s20
	s_and_b32 s28, s23, 31
	s_lshr_b32 s29, s23, 5
	s_lshl_b32 s28, s28, 6
	s_lshl_b32 s29, s29, 6
	s_mov_b32 s13, 0
	s_add_u32 s31, s29, 0x1140
	s_mul_i32 s12, s28, 0xa500
	s_lshl_b32 s31, s31, 2
	s_add_u32 s12, s12, s31
	s_add_u32 s24, s16, s12
	s_addc_u32 s25, s17, 0
	s_cmp_lt_u32 s23, 0xc00
	s_cbranch_scc0 .Lmyg_nl
	global_load_dword v184, v208, s[24:25]
	global_load_dword v185, v209, s[24:25]
	global_load_dword v186, v210, s[24:25]
	global_load_dword v187, v211, s[24:25]
	global_load_dword v188, v212, s[24:25]
	global_load_dword v189, v213, s[24:25]
	global_load_dword v190, v214, s[24:25]
	global_load_dword v191, v215, s[24:25]
	s_mul_i32 s23, s60, 2
	s_add_u32 s23, s23, s20
	s_and_b32 s28, s23, 31
	s_lshr_b32 s29, s23, 5
	s_lshl_b32 s28, s28, 6
	s_lshl_b32 s29, s29, 6
	s_mov_b32 s13, 0
	s_add_u32 s31, s29, 0x1140
	s_mul_i32 s12, s28, 0xa500
	s_lshl_b32 s31, s31, 2
	s_add_u32 s12, s12, s31
	s_add_u32 s24, s16, s12
	s_addc_u32 s25, s17, 0
	s_cmp_lt_u32 s23, 0xc00
	s_cbranch_scc0 .Lmyg_nl
	global_load_dword v192, v208, s[24:25]
	global_load_dword v193, v209, s[24:25]
	global_load_dword v194, v210, s[24:25]
	global_load_dword v195, v211, s[24:25]
	global_load_dword v196, v212, s[24:25]
	global_load_dword v197, v213, s[24:25]
	global_load_dword v198, v214, s[24:25]
	global_load_dword v199, v215, s[24:25]
	s_mul_i32 s23, s60, 3
	s_add_u32 s23, s23, s20
	s_and_b32 s28, s23, 31
	s_lshr_b32 s29, s23, 5
	s_lshl_b32 s28, s28, 6
	s_lshl_b32 s29, s29, 6
	s_mov_b32 s13, 0
	s_add_u32 s31, s29, 0x1140
	s_mul_i32 s12, s28, 0xa500
	s_lshl_b32 s31, s31, 2
	s_add_u32 s12, s12, s31
	s_add_u32 s24, s16, s12
	s_addc_u32 s25, s17, 0
	s_cmp_lt_u32 s23, 0xc00
	s_cbranch_scc0 .Lmyg_nl
	global_load_dword v200, v208, s[24:25]
	global_load_dword v201, v209, s[24:25]
	global_load_dword v202, v210, s[24:25]
	global_load_dword v203, v211, s[24:25]
	global_load_dword v204, v212, s[24:25]
	global_load_dword v205, v213, s[24:25]
	global_load_dword v206, v214, s[24:25]
	global_load_dword v207, v215, s[24:25]
; __device__ __forceinline__ void cvt_job(LAS unsigned char* lds, const float* src, bf16_t* dst, const float* kscale, int K, int Nsrc, int Ndst, int kind, int wv0, int bid_, int grd_) {
;     ...
;     { const int nl2 = tid >> 3, kc = (tid & 7) * 8; float w[8];
; #pragma unroll
;       for (int j = 0; j < 8; ++j) w[j] = tile[(kc + j) * 65 + nl2];
;       store8bf(dst + (size_t)(n0 + nl2) * K + k0 + kc, w); }
;     __syncthreads();
;   }
.Lmyg_nl:
	s_sub_u32 s20, s20, s21
	s_mov_b32 s23, 0
	s_add_u32 s23, s23, s20
	s_and_b32 s28, s23, 31
	s_lshr_b32 s29, s23, 5
	s_lshl_b32 s28, s28, 6
	s_lshl_b32 s29, s29, 6
	s_mul_i32 s12, s29, 0x800
	s_add_u32 s12, s12, s28
	s_lshl_b32 s12, s12, 1
	s_add_u32 s26, s18, s12
	s_addc_u32 s27, s19, 0
	s_cmp_lt_u32 s23, 0xc00
	s_cbranch_scc0 .Lmyg_sd
	ds_read_b32 v98, v217 offset:0
	ds_read_b32 v99, v217 offset:260
	ds_read_b32 v100, v217 offset:520
	ds_read_b32 v101, v217 offset:780
	ds_read_b32 v102, v217 offset:1040
	ds_read_b32 v103, v217 offset:1300
	ds_read_b32 v104, v217 offset:1560
	ds_read_b32 v105, v217 offset:1820
	s_waitcnt lgkmcnt(0)
	v_cvt_pk_bf16_f32 v130, v98, v99
	v_cvt_pk_bf16_f32 v131, v100, v101
	v_cvt_pk_bf16_f32 v132, v102, v103
	v_cvt_pk_bf16_f32 v133, v104, v105
	global_store_dwordx4 v234, v[130:133], s[26:27]
	s_mul_i32 s23, s60, 1
	s_add_u32 s23, s23, s20
	s_and_b32 s28, s23, 31
	s_lshr_b32 s29, s23, 5
	s_lshl_b32 s28, s28, 6
	s_lshl_b32 s29, s29, 6
	s_mul_i32 s12, s29, 0x800
	s_add_u32 s12, s12, s28
	s_lshl_b32 s12, s12, 1
	s_add_u32 s26, s18, s12
	s_addc_u32 s27, s19, 0
	s_cmp_lt_u32 s23, 0xc00
	s_cbranch_scc0 .Lmyg_sd
	ds_read_b32 v106, v217 offset:16640
	ds_read_b32 v107, v217 offset:16900
	ds_read_b32 v108, v217 offset:17160
	ds_read_b32 v109, v217 offset:17420
	ds_read_b32 v110, v217 offset:17680
	ds_read_b32 v111, v217 offset:17940
	ds_read_b32 v112, v217 offset:18200
	ds_read_b32 v113, v217 offset:18460
	s_waitcnt lgkmcnt(0)
	v_cvt_pk_bf16_f32 v134, v106, v107
	v_cvt_pk_bf16_f32 v135, v108, v109
	v_cvt_pk_bf16_f32 v136, v110, v111
	v_cvt_pk_bf16_f32 v137, v112, v113
	global_store_dwordx4 v234, v[134:137], s[26:27]
	s_mul_i32 s23, s60, 2
	s_add_u32 s23, s23, s20
	s_and_b32 s28, s23, 31
	s_lshr_b32 s29, s23, 5
	s_lshl_b32 s28, s28, 6
	s_lshl_b32 s29, s29, 6
	s_mul_i32 s12, s29, 0x800
	s_add_u32 s12, s12, s28
	s_lshl_b32 s12, s12, 1
	s_add_u32 s26, s18, s12
	s_addc_u32 s27, s19, 0
	s_cmp_lt_u32 s23, 0xc00
	s_cbranch_scc0 .Lmyg_sd
	ds_read_b32 v114, v217 offset:33280
	ds_read_b32 v115, v217 offset:33540
	ds_read_b32 v116, v217 offset:33800
	ds_read_b32 v117, v217 offset:34060
	ds_read_b32 v118, v217 offset:34320
	ds_read_b32 v119, v217 offset:34580
	ds_read_b32 v120, v217 offset:34840
	ds_read_b32 v121, v217 offset:35100
	s_waitcnt lgkmcnt(0)
	v_cvt_pk_bf16_f32 v138, v114, v115
	v_cvt_pk_bf16_f32 v139, v116, v117
	v_cvt_pk_bf16_f32 v140, v118, v119
	v_cvt_pk_bf16_f32 v141, v120, v121
	global_store_dwordx4 v234, v[138:141], s[26:27]
	s_mul_i32 s23, s60, 3
	s_add_u32 s23, s23, s20
	s_and_b32 s28, s23, 31
	s_lshr_b32 s29, s23, 5
	s_lshl_b32 s28, s28, 6
	s_lshl_b32 s29, s29, 6
	s_mul_i32 s12, s29, 0x800
	s_add_u32 s12, s12, s28
	s_lshl_b32 s12, s12, 1
	s_add_u32 s26, s18, s12
	s_addc_u32 s27, s19, 0
	s_cmp_lt_u32 s23, 0xc00
	s_cbranch_scc0 .Lmyg_sd
	ds_read_b32 v122, v217 offset:49920
	ds_read_b32 v123, v217 offset:50180
	ds_read_b32 v124, v217 offset:50440
	ds_read_b32 v125, v217 offset:50700
	ds_read_b32 v126, v217 offset:50960
	ds_read_b32 v127, v217 offset:51220
	ds_read_b32 v128, v217 offset:51480
	ds_read_b32 v129, v217 offset:51740
	s_waitcnt lgkmcnt(0)
	v_cvt_pk_bf16_f32 v142, v122, v123
	v_cvt_pk_bf16_f32 v143, v124, v125
	v_cvt_pk_bf16_f32 v144, v126, v127
	v_cvt_pk_bf16_f32 v145, v128, v129
	global_store_dwordx4 v234, v[142:145], s[26:27]
.Lmyg_sd:
	s_barrier
	s_add_u32 s20, s20, s21
	s_cmp_lt_u32 s20, 0xc00
	s_cbranch_scc0 .Lmyg_end
	s_waitcnt vmcnt(4)
	s_branch .Lmyg_loop
.Lmyg_end:
	s_waitcnt vmcnt(0)
.LBB0_106:
	s_mov_b32 s12, s82
	s_mov_b32 s1, -1
	s_ashr_i32 s13, s12, 31
	s_waitcnt vmcnt(1)
	v_mbcnt_lo_u32_b32 v1, s1, 0
	v_mbcnt_hi_u32_b32 v1, s1, v1
	v_or_b32_e32 v20, s0, v1
	s_waitcnt lgkmcnt(0)
	s_lshl_b64 s[2:3], s[12:13], 9
	s_mov_b32 s14, s60
	v_ashrrev_i32_e32 v21, 31, v20
	v_lshl_add_u64 v[18:19], s[2:3], 0, v[20:21]
	s_ashr_i32 s15, s14, 31
	s_mov_b64 s[16:17], 0x800000
	s_lshl_b64 s[10:11], s[14:15], 9
	v_cmp_gt_u64_e32 vcc, s[16:17], v[18:19]
	s_and_saveexec_b64 s[18:19], vcc
	s_cbranch_execz .LBB0_121
	s_load_dwordx2 s[20:21], s[54:55], 0x0
	s_lshl_b64 s[0:1], s[12:13], 12
	s_lshl_b64 s[4:5], s[14:15], 12
	s_add_u32 s4, s0, s4
	s_addc_u32 s5, s1, s5
	s_lshl_b64 s[22:23], s[14:15], 14
	s_lshl_b64 s[24:25], s[14:15], 10
	v_lshlrev_b64 v[2:3], 3, v[20:21]
	s_waitcnt lgkmcnt(0)
	s_add_u32 s26, s20, s22
	v_lshl_add_u64 v[4:5], s[4:5], 0, v[2:3]
	v_lshl_add_u64 v[2:3], s[0:1], 0, v[2:3]
	s_addc_u32 s27, s21, s23
	s_lshl_b64 s[0:1], s[12:13], 13
	s_lshl_b64 s[28:29], s[14:15], 15
	v_lshl_add_u64 v[26:27], v[20:21], 4, s[0:1]
	s_add_u32 s0, s24, s2
	s_mov_b64 s[4:5], 0x4900000
	s_addc_u32 s1, s25, s3
	v_lshl_add_u64 v[24:25], v[2:3], 0, s[4:5]
	v_lshl_add_u64 v[2:3], s[0:1], 0, v[20:21]
	s_mul_i32 s1, s14, 0x6000
	s_mul_hi_i32 s0, s14, 0x6000
	s_add_u32 s34, s20, s1
	s_mul_i32 s30, s14, 0x600
	s_addc_u32 s35, s21, s0
	s_mul_hi_i32 s31, s14, 0x600
	s_add_u32 s0, s30, s2
	v_lshl_add_u64 v[22:23], v[4:5], 0, s[4:5]
	v_mov_b64_e32 v[4:5], 0x4900000
	s_addc_u32 s1, s31, s3
	v_lshl_add_u64 v[28:29], v[2:3], 3, v[4:5]
	v_lshl_add_u64 v[2:3], s[0:1], 0, v[20:21]
	s_lshl_b64 s[0:1], s[14:15], 13
	v_lshl_add_u64 v[30:31], v[2:3], 3, v[4:5]
	s_add_u32 s36, s20, s0
	v_mov_b32_e32 v2, 0
	s_addc_u32 s37, s21, s1
	s_mov_b64 s[38:39], 0
	s_mov_b64 s[40:41], 0x7fffff
	v_mov_b64_e32 v[34:35], v[18:19]
	v_mov_b32_e32 v3, v2
	v_mov_b32_e32 v4, v2
	v_mov_b32_e32 v5, v2
	v_mov_b32_e32 v6, v2
	v_mov_b32_e32 v7, v2
	v_mov_b32_e32 v8, v2
	s_waitcnt vmcnt(0)
	v_mov_b32_e32 v9, v2
	v_mov_b32_e32 v10, v2
	v_mov_b32_e32 v11, v2
	v_mov_b32_e32 v12, v2
	v_mov_b32_e32 v13, v2
	s_branch .LBB0_109

; #define LAS __attribute__((address_space(3)))
; __device__ __forceinline__ int otid(int wv0) { int t = (wv0 << 6) | olane(); asm volatile("" : "+v"(t)); return t; }
; __device__ __forceinline__ int rope_src(int j) { return (j & 1) ? 32 + (j >> 1) : (j >> 1); }
; #define CVT_LOAD(t_) do { const int k0_ = ((t_) % nkt) * 64, n0_ = ((t_) / nkt) * 64; const int sn = srcmap(kind, n0_ + nl); \
;     _Pragma("unroll") for (int i = 0; i < 8; ++i) { const int kl = kb + 8 * i; v[i] = 0.f; \
;       if (sn >= 0) { v[i] = src[(size_t)(k0_ + kl) * Nsrc + sn]; if (kscale) v[i] *= kscale[k0_ + kl]; } } } while (0)
; __device__ __forceinline__ int srcmap(int kind, int n) {
;   if (kind == 0) return n;
;   if (kind == 1) {
;     if (n < C_KR) return n;
;     if (n < C_HU) return 2304 + rope_src(n - C_KR);
;     if (n < C_CQ) return n - C_HU + 2368;
;     if (n < C_CKV) return n - C_CQ + 1280;
;     if (n < C_HV) return n - C_CKV + 1792;
;     if (n < LDH) return n;
;     return -1;
;   }
;   if (kind == 2) return 4416 + n;
;   if (kind == 4) { const int pn = n >> 8, lc = n & 255; return lc < 128 ? 128 * pn + lc : DFF + 128 * pn + (lc - 128); }
;   { const int hd = n / 192, c = n % 192; if (c < 128) return n; return hd * 192 + 128 + rope_src(c - 128); }
; }
; __device__ __forceinline__ void cvt_job(LAS unsigned char* lds, const float* src, bf16_t* dst, const float* kscale, int K, int Nsrc, int Ndst, int kind, int wv0, int bid_, int grd_) {
;   LAS float* tile = (LAS float*)lds;
;   const int tid = otid(wv0), nkt = K / 64, ntile = (Ndst / 64) * nkt;
;   if (bid_ < 0) return;
;   const int nl = tid & 63, kb = tid >> 6;
;   float v[8];
;     ...
;   if (bid_ < ntile) CVT_LOAD(bid_);
.LBB0_1512:
	s_mov_b32 s14, s82
	s_mov_b32 s1, s60
	s_load_dwordx2 s[16:17], s[54:55], 0x10
	s_waitcnt lgkmcnt(0)
	s_add_u32 s16, s16, 0x5280000
	s_addc_u32 s17, s17, 0
	s_mov_b64 s[18:19], s[8:9]
	v_mbcnt_lo_u32_b32 v235, -1, 0
	v_mbcnt_hi_u32_b32 v235, -1, v235
	v_or_b32_e32 v235, s22, v235
	v_and_b32_e32 v236, 63, v235
	v_lshrrev_b32_e32 v216, 6, v235
	s_mov_b32 s30, 0xa500
	v_mul_lo_u32 v208, v216, s30
	v_lshrrev_b32_e32 v147, 1, v236
	v_and_b32_e32 v148, 1, v236
	v_lshl_add_u32 v147, v148, 5, v147
	v_lshl_add_u32 v146, v147, 2, v208
	v_lshl_add_u32 v208, v236, 2, v208
	v_add_u32_e32 v209, 0x52800, v208
	v_add_u32_e32 v210, 0xa5000, v208
	v_add_u32_e32 v211, 0xf7800, v208
	v_add_u32_e32 v212, 0x14a000, v208
	v_add_u32_e32 v213, 0x19c800, v208
	v_add_u32_e32 v214, 0x1ef000, v208
	v_add_u32_e32 v215, 0x241800, v208
	v_add_u32_e32 v147, 0x52800, v146
	v_add_u32_e32 v148, 0xa5000, v146
	v_add_u32_e32 v149, 0xf7800, v146
	v_add_u32_e32 v150, 0x14a000, v146
	v_add_u32_e32 v151, 0x19c800, v146
	v_add_u32_e32 v152, 0x1ef000, v146
	v_add_u32_e32 v153, 0x241800, v146
	v_mul_u32_u24_e32 v216, 65, v216
	v_add_lshl_u32 v216, v216, v236, 2
	v_and_b32_e32 v236, 7, v235
	v_lshlrev_b32_e32 v236, 3, v236
	v_lshrrev_b32_e32 v235, 3, v235
	v_mul_u32_u24_e32 v217, 65, v236
	v_add_lshl_u32 v217, v217, v235, 2
	s_movk_i32 s30, 0x800
	v_mul_lo_u32 v234, v235, s30
	v_add_lshl_u32 v234, v234, v236, 1
	s_mov_b32 s20, s82
	s_lshl_b32 s21, s60, 2
	s_mov_b32 s23, 0
	s_add_u32 s23, s23, s20
	s_and_b32 s28, s23, 31
	s_lshr_b32 s29, s23, 5
	s_lshl_b32 s28, s28, 6
	s_lshl_b32 s29, s29, 6
	s_mov_b32 s13, 0
	s_mov_b32 s31, s29
	s_add_u32 s12, s29, 0x400
	s_cmp_ge_u32 s29, 0x540
	s_cselect_b32 s31, s12, s31
	s_sub_u32 s12, s29, 0x440
	s_cmp_ge_u32 s29, 0x940
	s_cselect_b32 s31, s12, s31
	s_cmp_ge_u32 s29, 0xd40
	s_cselect_b32 s31, s29, s31
	s_cmp_eq_u32 s29, 0x500
	s_cselect_b32 s31, 0x900, s31
	s_cselect_b32 s13, 1, s13
	s_cmp_ge_u32 s29, 0x1140
	s_cselect_b32 s13, 2, s13
	s_cselect_b32 s31, 0, s31
	s_mul_i32 s12, s28, 0xa500
	s_lshl_b32 s31, s31, 2
	s_add_u32 s12, s12, s31
	s_add_u32 s24, s16, s12
	s_addc_u32 s25, s17, 0
	s_cmp_lt_u32 s23, 0x900
	s_cbranch_scc0 .Lmxa_pl
	s_cmp_eq_u32 s13, 0
	s_cbranch_scc1 .Lmxa_p1
	s_cmp_eq_u32 s13, 1
	s_cbranch_scc1 .Lmxa_r1
	v_mov_b32_e32 v176, 0
	v_mov_b32_e32 v177, 0
	v_mov_b32_e32 v178, 0
	v_mov_b32_e32 v179, 0
	v_mov_b32_e32 v180, 0
	v_mov_b32_e32 v181, 0
	v_mov_b32_e32 v182, 0
	v_mov_b32_e32 v183, 0
	s_branch .Lmxa_x1

; #define LAS __attribute__((address_space(3)))
; __device__ __forceinline__ int otid(int wv0) { int t = (wv0 << 6) | olane(); asm volatile("" : "+v"(t)); return t; }
; __device__ __forceinline__ int rope_src(int j) { return (j & 1) ? 32 + (j >> 1) : (j >> 1); }
; #define CVT_LOAD(t_) do { const int k0_ = ((t_) % nkt) * 64, n0_ = ((t_) / nkt) * 64; const int sn = srcmap(kind, n0_ + nl); \
;     _Pragma("unroll") for (int i = 0; i < 8; ++i) { const int kl = kb + 8 * i; v[i] = 0.f; \
;       if (sn >= 0) { v[i] = src[(size_t)(k0_ + kl) * Nsrc + sn]; if (kscale) v[i] *= kscale[k0_ + kl]; } } } while (0)
; __device__ __forceinline__ int srcmap(int kind, int n) {
;     ...
;   if (kind == 2) return 4416 + n;
;   if (kind == 4) { const int pn = n >> 8, lc = n & 255; return lc < 128 ? 128 * pn + lc : DFF + 128 * pn + (lc - 128); }
;   { const int hd = n / 192, c = n % 192; if (c < 128) return n; return hd * 192 + 128 + rope_src(c - 128); }
; }
; __device__ __forceinline__ void cvt_job(LAS unsigned char* lds, const float* src, bf16_t* dst, const float* kscale, int K, int Nsrc, int Ndst, int kind, int wv0, int bid_, int grd_) {
;   LAS float* tile = (LAS float*)lds;
;   const int tid = otid(wv0), nkt = K / 64, ntile = (Ndst / 64) * nkt;
;   if (bid_ < 0) return;
;   const int nl = tid & 63, kb = tid >> 6;
;   float v[8];
;     ...
;   if (bid_ < ntile) CVT_LOAD(bid_);
.Lmxa_end:
	s_waitcnt vmcnt(0)
	s_add_u32 s18, s8, 0x1200000
	s_addc_u32 s19, s9, 0
	v_mbcnt_lo_u32_b32 v235, -1, 0
	v_mbcnt_hi_u32_b32 v235, -1, v235
	v_or_b32_e32 v235, s22, v235
	v_and_b32_e32 v236, 63, v235
	v_lshrrev_b32_e32 v216, 6, v235
	s_mov_b32 s30, 0xa500
	v_mul_lo_u32 v208, v216, s30
	v_lshl_add_u32 v208, v236, 2, v208
	v_add_u32_e32 v209, 0x52800, v208
	v_add_u32_e32 v210, 0xa5000, v208
	v_add_u32_e32 v211, 0xf7800, v208
	v_add_u32_e32 v212, 0x14a000, v208
	v_add_u32_e32 v213, 0x19c800, v208
	v_add_u32_e32 v214, 0x1ef000, v208
	v_add_u32_e32 v215, 0x241800, v208
	v_mul_u32_u24_e32 v216, 65, v216
	v_add_lshl_u32 v216, v216, v236, 2
	v_and_b32_e32 v236, 7, v235
	v_lshlrev_b32_e32 v236, 3, v236
	v_lshrrev_b32_e32 v235, 3, v235
	v_mul_u32_u24_e32 v217, 65, v236
	v_add_lshl_u32 v217, v217, v235, 2
	s_movk_i32 s30, 0x800
	v_mul_lo_u32 v234, v235, s30
	v_add_lshl_u32 v234, v234, v236, 1
	s_mov_b32 s20, s82
	s_lshl_b32 s21, s60, 2
	s_mov_b32 s23, 0
	s_add_u32 s23, s23, s20
	s_and_b32 s28, s23, 31
	s_lshr_b32 s29, s23, 5
	s_lshl_b32 s28, s28, 6
	s_lshl_b32 s29, s29, 6
	s_mov_b32 s13, 0
	s_add_u32 s31, s29, 0x1140
	s_mul_i32 s12, s28, 0xa500
	s_lshl_b32 s31, s31, 2
	s_add_u32 s12, s12, s31
	s_add_u32 s24, s16, s12
	s_addc_u32 s25, s17, 0
	s_cmp_lt_u32 s23, 0xc00
	s_cbranch_scc0 .Lmxg_pl
	global_load_dword v176, v208, s[24:25]
	global_load_dword v177, v209, s[24:25]
	global_load_dword v178, v210, s[24:25]
	global_load_dword v179, v211, s[24:25]
	global_load_dword v180, v212, s[24:25]
	global_load_dword v181, v213, s[24:25]
	global_load_dword v182, v214, s[24:25]
	global_load_dword v183, v215, s[24:25]
	s_mul_i32 s23, s60, 1
	s_add_u32 s23, s23, s20
	s_and_b32 s28, s23, 31
	s_lshr_b32 s29, s23, 5
	s_lshl_b32 s28, s28, 6
	s_lshl_b32 s29, s29, 6
	s_mov_b32 s13, 0
	s_add_u32 s31, s29, 0x1140
	s_mul_i32 s12, s28, 0xa500
	s_lshl_b32 s31, s31, 2
	s_add_u32 s12, s12, s31
	s_add_u32 s24, s16, s12
	s_addc_u32 s25, s17, 0
	s_cmp_lt_u32 s23, 0xc00
	s_cbranch_scc0 .Lmxg_pl
	global_load_dword v184, v208, s[24:25]
	global_load_dword v185, v209, s[24:25]
	global_load_dword v186, v210, s[24:25]
	global_load_dword v187, v211, s[24:25]
	global_load_dword v188, v212, s[24:25]
	global_load_dword v189, v213, s[24:25]
	global_load_dword v190, v214, s[24:25]
	global_load_dword v191, v215, s[24:25]
	s_mul_i32 s23, s60, 2
	s_add_u32 s23, s23, s20
	s_and_b32 s28, s23, 31
	s_lshr_b32 s29, s23, 5
	s_lshl_b32 s28, s28, 6
	s_lshl_b32 s29, s29, 6
	s_mov_b32 s13, 0
	s_add_u32 s31, s29, 0x1140
	s_mul_i32 s12, s28, 0xa500
	s_lshl_b32 s31, s31, 2
	s_add_u32 s12, s12, s31
	s_add_u32 s24, s16, s12
	s_addc_u32 s25, s17, 0
	s_cmp_lt_u32 s23, 0xc00
	s_cbranch_scc0 .Lmxg_pl
	global_load_dword v192, v208, s[24:25]
	global_load_dword v193, v209, s[24:25]
	global_load_dword v194, v210, s[24:25]
	global_load_dword v195, v211, s[24:25]
	global_load_dword v196, v212, s[24:25]
	global_load_dword v197, v213, s[24:25]
	global_load_dword v198, v214, s[24:25]
	global_load_dword v199, v215, s[24:25]
	s_mul_i32 s23, s60, 3
	s_add_u32 s23, s23, s20
	s_and_b32 s28, s23, 31
	s_lshr_b32 s29, s23, 5
	s_lshl_b32 s28, s28, 6
	s_lshl_b32 s29, s29, 6
	s_mov_b32 s13, 0
	s_add_u32 s31, s29, 0x1140
	s_mul_i32 s12, s28, 0xa500
	s_lshl_b32 s31, s31, 2
	s_add_u32 s12, s12, s31
	s_add_u32 s24, s16, s12
	s_addc_u32 s25, s17, 0
	s_cmp_lt_u32 s23, 0xc00
	s_cbranch_scc0 .Lmxg_pl
	global_load_dword v200, v208, s[24:25]
	global_load_dword v201, v209, s[24:25]
	global_load_dword v202, v210, s[24:25]
	global_load_dword v203, v211, s[24:25]
	global_load_dword v204, v212, s[24:25]
	global_load_dword v205, v213, s[24:25]
	global_load_dword v206, v214, s[24:25]
	global_load_dword v207, v215, s[24:25]

; #define LAS __attribute__((address_space(3)))
; __device__ __forceinline__ int otid(int wv0) { int t = (wv0 << 6) | olane(); asm volatile("" : "+v"(t)); return t; }
; __device__ __forceinline__ unsigned xb_add(unsigned* p, unsigned v) { return __hip_atomic_fetch_add(p, v, __ATOMIC_RELAXED, __HIP_MEMORY_SCOPE_AGENT); }
; __device__ __forceinline__ unsigned xb_xcc_id() { return (unsigned)__builtin_amdgcn_s_getreg((3 << 11) | 20) & 0xFu; }
; __device__ __forceinline__ void xcd_barrier(unsigned* bar, volatile LAS unsigned* st, int wv0) {
;     asm volatile("s_waitcnt vmcnt(0)" ::: "memory");
;     __syncthreads();
;     if (otid(wv0) == 0) {
;         const unsigned x = xb_xcc_id();
;         __builtin_amdgcn_s_waitcnt(0);
;         unsigned nloc = st[0], nx = st[1];
;         if (nloc == 0u) { xcd_barrier_complete(bar, x, nloc, nx); st[0] = nloc; st[1] = nx; }
;         const unsigned old = xb_add(&bar[XB_XSUB(x)], 1u);
.Lmxg_end:
	s_waitcnt vmcnt(0)
.LBB0_1604:
	s_mov_b32 s0, -1
	s_waitcnt vmcnt(0)
	s_barrier
	s_waitcnt vmcnt(1)
	v_mbcnt_lo_u32_b32 v0, s0, 0
	v_mbcnt_hi_u32_b32 v0, s0, v0
	v_or_b32_e32 v0, s22, v0
	s_nop 0
	v_cmp_eq_u32_e32 vcc, 0, v0
	s_and_saveexec_b64 s[0:1], vcc
	s_xor_b64 s[2:3], exec, s[0:1]
	s_cbranch_execnz .LBB0_1605
	s_getpc_b64 s[98:99]
